# one-barrier attention loop plus one static s_setprio 1 for waves 4-7 at the attention unit head (the waves may now drift within an iteration, so the younger half runs ahead)
# baseline (speedup 1.0000x reference)
; DI void attn_unit(const Params& p, int l, int b, int kvh, int qb, bool isctx, ldsp_t smem) {
;     int tid = threadIdx.x;
;     asm volatile("" : "+v"(tid));
;     const int wid = tid >> 6, lane = tid & 63, r = lane & 31, hh = lane >> 5;
;     const int head = kvh * 4 + (wid >> 1);
;     const int t0 = qb * 64 + (wid & 1) * 32;
.LBB0_163:
	v_readfirstlane_b32 s100, v252
	s_nop 3
	s_lshr_b32 s100, s100, 6
	s_cmp_ge_u32 s100, 4
	s_cbranch_scc0 .Lsprio_done_attn
	s_setprio 1
